# GEMM loops: LDS-DMA loads use SGPR-base + 32-bit VGPR offset form (no per-load 64-bit VALU address adds); no setprio; RET edits
# speedup vs baseline: 1.0117x; 1.0117x over previous
; #define PG8_STAGE(bufoff, gbase, voff) do { _Pragma("unroll") for (int _i = 0; _i < 2; ++_i) \
;         __builtin_amdgcn_global_load_lds((const unsigned*)((const char*)(gbase) + (voff)[_i]), (LAS unsigned*)(lds + (bufoff) + ldsw + _i * 8192), 16, 0, 0); } while (0)
; #define PG8_LDA(dst, b, h) do { _Pragma("unroll") for (int m = 0; m < 4; ++m) _Pragma("unroll") for (int k = 0; k < 2; ++k) dst[m][k] = *(const LAS bf16x8*)(lds + PG8_SA(b, h) + aoff + m * 2048 + k * 1024); } while (0)
; #define PG8_LDB(dst, b, h) do { _Pragma("unroll") for (int n = 0; n < 2; ++n) _Pragma("unroll") for (int k = 0; k < 2; ++k) dst[n][k] = *(const LAS bf16x8*)(lds + PG8_SB(b, h) + boff + n * 2048 + k * 1024); } while (0)
; #define PG8_MMA(ai, bj, At, Bt) do { __builtin_amdgcn_s_setprio(1); _Pragma("unroll") for (int m = 0; m < 4; ++m) _Pragma("unroll") for (int n = 0; n < 2; ++n) _Pragma("unroll") for (int k = 0; k < 2; ++k) \
;         acc[ai][bj][m][n] = __builtin_amdgcn_mfma_f32_16x16x32_bf16(Bt[n][k], At[m][k], acc[ai][bj][m][n], 0, 0, 0); __builtin_amdgcn_s_setprio(0); } while (0)
; #define PG8_WAIT_V(n) asm volatile("s_waitcnt vmcnt(" #n ")" ::: "memory")
; #define PG8_WAIT_L(n) asm volatile("s_waitcnt lgkmcnt(" #n ")" ::: "memory")
; #define PG8_BAR __builtin_amdgcn_s_barrier()
; #define PG8_SCHED __builtin_amdgcn_sched_barrier(0)
; template <class Epi, class Sched>
; __device__ __forceinline__ void gemm_phase(LAS unsigned char* lds, const Gemm g, const Sched& S, const Epi& E) {
;     ...
;             PG8_LDB(B0, 0, 0); PG8_SCHED; PG8_LDA(At, 0, 0); PG8_STAGE(PG8_SA(1, 1), a1 + hstep, voffA);
;             PG8_WAIT_L(8); PG8_BAR; PG8_WAIT_L(0); PG8_MMA(0, 0, At, B0); PG8_BAR; PG8_SCHED;
;             PG8_LDB(B1, 0, 1); PG8_STAGE(PG8_SB(0, 0), b2, voffB);
;             PG8_BAR; PG8_WAIT_L(0); PG8_MMA(0, 1, At, B1); PG8_BAR;
;             PG8_LDA(At, 0, 1); PG8_STAGE(PG8_SA(0, 0), a2, voffA);
;             PG8_BAR; PG8_WAIT_L(0); PG8_MMA(1, 0, At, B0); PG8_BAR; PG8_SCHED;
;             PG8_STAGE(PG8_SB(0, 1), b2 + hstep, voffB);
;             PG8_WAIT_V(6); PG8_BAR; PG8_MMA(1, 1, At, B1); PG8_BAR;
.LBB0_232:
	s_add_i32 s33, s29, 2
	s_add_u32 s30, s26, 0x80
	s_addc_u32 s31, s27, 0
	s_add_i32 s42, 0, 0x10000
	v_add_u32_e32 v140, s42, v191
	ds_read_b128 v[128:131], v140
	ds_read_b128 v[132:135], v140 offset:1024
	ds_read_b128 v[136:139], v140 offset:2048
	ds_read_b128 v[140:143], v140 offset:3072
	s_cmp_eq_u32 s76, s29
	s_cselect_b32 s31, s1, s31
	s_cselect_b32 s30, s0, s30
	s_cselect_b32 s35, s9, s25
	s_cselect_b32 s34, s8, s24
	s_add_i32 m0, s67, 0xc000
	ds_read_b128 v[144:147], v235
	ds_read_b128 v[148:151], v235 offset:1024
	ds_read_b128 v[152:155], v235 offset:2048
	ds_read_b128 v[156:159], v235 offset:3072
	ds_read_b128 v[160:163], v235 offset:4096
	ds_read_b128 v[164:167], v235 offset:5120
	ds_read_b128 v[168:171], v235 offset:6144
	ds_read_b128 v[172:175], v235 offset:7168
	global_load_lds_dwordx4 v194, s[26:27]
	s_add_i32 m0, s67, 0xe000
	s_nop 0
	global_load_lds_dwordx4 v192, s[26:27]
	s_waitcnt lgkmcnt(8)
	s_barrier
	s_waitcnt lgkmcnt(0)
	s_waitcnt lgkmcnt(0)
	v_mfma_f32_16x16x32_bf16 v[120:123], v[128:131], v[144:147], v[120:123]
	v_mfma_f32_16x16x32_bf16 v[112:115], v[136:139], v[144:147], v[112:115]
	v_mfma_f32_16x16x32_bf16 v[104:107], v[128:131], v[152:155], v[104:107]
	v_mfma_f32_16x16x32_bf16 v[96:99], v[136:139], v[152:155], v[96:99]
	v_mfma_f32_16x16x32_bf16 v[88:91], v[128:131], v[160:163], v[88:91]
	v_mfma_f32_16x16x32_bf16 v[80:83], v[136:139], v[160:163], v[80:83]
	v_mfma_f32_16x16x32_bf16 v[72:75], v[128:131], v[168:171], v[72:75]
	v_mfma_f32_16x16x32_bf16 v[64:67], v[136:139], v[168:171], v[64:67]
	v_mfma_f32_16x16x32_bf16 v[120:123], v[132:135], v[148:151], v[120:123]
	v_mfma_f32_16x16x32_bf16 v[112:115], v[140:143], v[148:151], v[112:115]
	v_mfma_f32_16x16x32_bf16 v[104:107], v[132:135], v[156:159], v[104:107]
	v_mfma_f32_16x16x32_bf16 v[96:99], v[140:143], v[156:159], v[96:99]
	v_mfma_f32_16x16x32_bf16 v[88:91], v[132:135], v[164:167], v[88:91]
	v_mfma_f32_16x16x32_bf16 v[80:83], v[140:143], v[164:167], v[80:83]
	v_mfma_f32_16x16x32_bf16 v[72:75], v[132:135], v[172:175], v[72:75]
	v_mfma_f32_16x16x32_bf16 v[64:67], v[140:143], v[172:175], v[64:67]
	s_barrier
	s_add_i32 s29, 0, 0x14000
	s_add_i32 s42, s42, s66
	v_add_u32_e32 v200, s29, v191
	s_mov_b32 m0, s42
	ds_read_b128 v[176:179], v200
	ds_read_b128 v[180:183], v200 offset:1024
	ds_read_b128 v[196:199], v200 offset:2048
	ds_read_b128 v[200:203], v200 offset:3072
	s_add_u32 s36, s34, 0x80
	s_addc_u32 s37, s35, 0
	global_load_lds_dwordx4 v188, s[34:35]
	s_add_i32 m0, s42, 0x2000
	s_nop 0
	global_load_lds_dwordx4 v184, s[34:35]
	s_barrier
	s_waitcnt lgkmcnt(0)
	s_waitcnt lgkmcnt(0)
	v_mfma_f32_16x16x32_bf16 v[124:127], v[176:179], v[144:147], v[124:127]
	v_mfma_f32_16x16x32_bf16 v[116:119], v[196:199], v[144:147], v[116:119]
	v_mfma_f32_16x16x32_bf16 v[108:111], v[176:179], v[152:155], v[108:111]
	v_mfma_f32_16x16x32_bf16 v[100:103], v[196:199], v[152:155], v[100:103]
	v_mfma_f32_16x16x32_bf16 v[92:95], v[176:179], v[160:163], v[92:95]
	v_mfma_f32_16x16x32_bf16 v[84:87], v[196:199], v[160:163], v[84:87]
	v_mfma_f32_16x16x32_bf16 v[76:79], v[176:179], v[168:171], v[76:79]
	v_mfma_f32_16x16x32_bf16 v[68:71], v[196:199], v[168:171], v[68:71]
	v_mfma_f32_16x16x32_bf16 v[124:127], v[180:183], v[148:151], v[124:127]
	v_mfma_f32_16x16x32_bf16 v[116:119], v[200:203], v[148:151], v[116:119]
	v_mfma_f32_16x16x32_bf16 v[108:111], v[180:183], v[156:159], v[108:111]
	v_mfma_f32_16x16x32_bf16 v[100:103], v[200:203], v[156:159], v[100:103]
	v_mfma_f32_16x16x32_bf16 v[92:95], v[180:183], v[164:167], v[92:95]
	v_mfma_f32_16x16x32_bf16 v[84:87], v[200:203], v[164:167], v[84:87]
	v_mfma_f32_16x16x32_bf16 v[76:79], v[180:183], v[172:175], v[76:79]
	v_mfma_f32_16x16x32_bf16 v[68:71], v[200:203], v[172:175], v[68:71]
	s_mov_b32 m0, s67
	s_barrier
	ds_read_b128 v[144:147], v235 offset:16384
	ds_read_b128 v[148:151], v235 offset:17408
	ds_read_b128 v[152:155], v235 offset:18432
	ds_read_b128 v[156:159], v235 offset:19456
	ds_read_b128 v[160:163], v235 offset:20480
	ds_read_b128 v[164:167], v235 offset:21504
	ds_read_b128 v[168:171], v235 offset:22528
	ds_read_b128 v[172:175], v235 offset:23552
	s_add_u32 s54, s30, 0x80
	s_addc_u32 s55, s31, 0
	global_load_lds_dwordx4 v188, s[30:31]
	s_mov_b32 m0, s68
	s_nop 0
	global_load_lds_dwordx4 v184, s[30:31]
	s_barrier
	s_waitcnt lgkmcnt(0)
	s_waitcnt lgkmcnt(0)
	v_mfma_f32_16x16x32_bf16 v[56:59], v[128:131], v[144:147], v[56:59]
	v_mfma_f32_16x16x32_bf16 v[48:51], v[136:139], v[144:147], v[48:51]
	v_mfma_f32_16x16x32_bf16 v[40:43], v[128:131], v[152:155], v[40:43]
	v_mfma_f32_16x16x32_bf16 v[32:35], v[136:139], v[152:155], v[32:35]
	v_mfma_f32_16x16x32_bf16 v[24:27], v[128:131], v[160:163], v[24:27]
	v_mfma_f32_16x16x32_bf16 v[16:19], v[136:139], v[160:163], v[16:19]
	v_mfma_f32_16x16x32_bf16 v[8:11], v[128:131], v[168:171], v[8:11]
	v_mfma_f32_16x16x32_bf16 v[0:3], v[136:139], v[168:171], v[0:3]
	v_mfma_f32_16x16x32_bf16 v[56:59], v[132:135], v[148:151], v[56:59]
	v_mfma_f32_16x16x32_bf16 v[48:51], v[140:143], v[148:151], v[48:51]
	v_mfma_f32_16x16x32_bf16 v[40:43], v[132:135], v[156:159], v[40:43]
	v_mfma_f32_16x16x32_bf16 v[32:35], v[140:143], v[156:159], v[32:35]
	v_mfma_f32_16x16x32_bf16 v[24:27], v[132:135], v[164:167], v[24:27]
	v_mfma_f32_16x16x32_bf16 v[16:19], v[140:143], v[164:167], v[16:19]
	v_mfma_f32_16x16x32_bf16 v[8:11], v[132:135], v[172:175], v[8:11]
	v_mfma_f32_16x16x32_bf16 v[0:3], v[140:143], v[172:175], v[0:3]
	s_barrier
	s_add_u32 s34, s34, s12
	s_addc_u32 s35, s35, s13
	s_add_u32 s84, s34, 0x80
	s_addc_u32 s85, s35, 0
	s_add_i32 s29, s29, s66
	s_mov_b32 m0, s29
	s_nop 0
	global_load_lds_dwordx4 v188, s[34:35]
	s_add_i32 m0, s29, 0x2000
	s_nop 0
	global_load_lds_dwordx4 v184, s[34:35]
	s_waitcnt vmcnt(6)
	s_barrier
; #define PG8_STAGE(bufoff, gbase, voff) do { _Pragma("unroll") for (int _i = 0; _i < 2; ++_i) \
;         __builtin_amdgcn_global_load_lds((const unsigned*)((const char*)(gbase) + (voff)[_i]), (LAS unsigned*)(lds + (bufoff) + ldsw + _i * 8192), 16, 0, 0); } while (0)
; #define PG8_LDA(dst, b, h) do { _Pragma("unroll") for (int m = 0; m < 4; ++m) _Pragma("unroll") for (int k = 0; k < 2; ++k) dst[m][k] = *(const LAS bf16x8*)(lds + PG8_SA(b, h) + aoff + m * 2048 + k * 1024); } while (0)
; #define PG8_LDB(dst, b, h) do { _Pragma("unroll") for (int n = 0; n < 2; ++n) _Pragma("unroll") for (int k = 0; k < 2; ++k) dst[n][k] = *(const LAS bf16x8*)(lds + PG8_SB(b, h) + boff + n * 2048 + k * 1024); } while (0)
; #define PG8_MMA(ai, bj, At, Bt) do { __builtin_amdgcn_s_setprio(1); _Pragma("unroll") for (int m = 0; m < 4; ++m) _Pragma("unroll") for (int n = 0; n < 2; ++n) _Pragma("unroll") for (int k = 0; k < 2; ++k) \
;         acc[ai][bj][m][n] = __builtin_amdgcn_mfma_f32_16x16x32_bf16(Bt[n][k], At[m][k], acc[ai][bj][m][n], 0, 0, 0); __builtin_amdgcn_s_setprio(0); } while (0)
; #define PG8_WAIT_V(n) asm volatile("s_waitcnt vmcnt(" #n ")" ::: "memory")
; #define PG8_WAIT_L(n) asm volatile("s_waitcnt lgkmcnt(" #n ")" ::: "memory")
; #define PG8_BAR __builtin_amdgcn_s_barrier()
; #define PG8_SCHED __builtin_amdgcn_sched_barrier(0)
; template <class Epi, class Sched>
; __device__ __forceinline__ void gemm_phase(LAS unsigned char* lds, const Gemm g, const Sched& S, const Epi& E) {
;     ...
;             PG8_WAIT_V(6); PG8_BAR; PG8_MMA(1, 1, At, B1); PG8_BAR;
;             PG8_LDB(B0, 1, 0); PG8_SCHED; PG8_LDA(At, 1, 0); PG8_STAGE(PG8_SA(0, 1), a2 + hstep, voffA);
;             PG8_WAIT_L(8); PG8_BAR; PG8_WAIT_L(0); PG8_MMA(0, 0, At, B0); PG8_BAR; PG8_SCHED;
;             PG8_LDB(B1, 1, 1); PG8_STAGE(PG8_SB(1, 0), b3, voffB);
	v_mfma_f32_16x16x32_bf16 v[60:63], v[176:179], v[144:147], v[60:63]
	v_mfma_f32_16x16x32_bf16 v[52:55], v[196:199], v[144:147], v[52:55]
	v_mfma_f32_16x16x32_bf16 v[44:47], v[176:179], v[152:155], v[44:47]
	v_mfma_f32_16x16x32_bf16 v[36:39], v[196:199], v[152:155], v[36:39]
	v_mfma_f32_16x16x32_bf16 v[28:31], v[176:179], v[160:163], v[28:31]
	v_mfma_f32_16x16x32_bf16 v[20:23], v[196:199], v[160:163], v[20:23]
	v_mfma_f32_16x16x32_bf16 v[12:15], v[176:179], v[168:171], v[12:15]
	v_mfma_f32_16x16x32_bf16 v[4:7], v[196:199], v[168:171], v[4:7]
	v_mfma_f32_16x16x32_bf16 v[60:63], v[180:183], v[148:151], v[60:63]
	v_mfma_f32_16x16x32_bf16 v[52:55], v[200:203], v[148:151], v[52:55]
	v_mfma_f32_16x16x32_bf16 v[44:47], v[180:183], v[156:159], v[44:47]
	v_mfma_f32_16x16x32_bf16 v[36:39], v[200:203], v[156:159], v[36:39]
	v_mfma_f32_16x16x32_bf16 v[28:31], v[180:183], v[164:167], v[28:31]
	v_mfma_f32_16x16x32_bf16 v[20:23], v[200:203], v[164:167], v[20:23]
	v_mfma_f32_16x16x32_bf16 v[12:15], v[180:183], v[172:175], v[12:15]
	v_mfma_f32_16x16x32_bf16 v[4:7], v[200:203], v[172:175], v[4:7]
	s_add_i32 s29, 0, 0x18000
	v_add_u32_e32 v140, s29, v191
	s_barrier
	ds_read_b128 v[128:131], v140
	ds_read_b128 v[132:135], v140 offset:1024
	ds_read_b128 v[136:139], v140 offset:2048
	ds_read_b128 v[140:143], v140 offset:3072
	s_add_u32 s30, s30, s12
	s_addc_u32 s31, s31, s13
	s_mov_b32 m0, s69
	ds_read_b128 v[144:147], v235 offset:32768
	ds_read_b128 v[148:151], v235 offset:33792
	ds_read_b128 v[152:155], v235 offset:34816
	ds_read_b128 v[156:159], v235 offset:35840
	ds_read_b128 v[160:163], v235 offset:36864
	ds_read_b128 v[164:167], v235 offset:37888
	ds_read_b128 v[168:171], v235 offset:38912
	ds_read_b128 v[172:175], v235 offset:39936
	global_load_lds_dwordx4 v188, s[30:31]
	s_mov_b32 m0, s70
	s_nop 0
	global_load_lds_dwordx4 v184, s[30:31]
	s_waitcnt lgkmcnt(8)
	s_barrier
	s_waitcnt lgkmcnt(0)
	s_waitcnt lgkmcnt(0)
	v_mfma_f32_16x16x32_bf16 v[120:123], v[128:131], v[144:147], v[120:123]
	v_mfma_f32_16x16x32_bf16 v[112:115], v[136:139], v[144:147], v[112:115]
	v_mfma_f32_16x16x32_bf16 v[104:107], v[128:131], v[152:155], v[104:107]
	v_mfma_f32_16x16x32_bf16 v[96:99], v[136:139], v[152:155], v[96:99]
	v_mfma_f32_16x16x32_bf16 v[88:91], v[128:131], v[160:163], v[88:91]
	v_mfma_f32_16x16x32_bf16 v[80:83], v[136:139], v[160:163], v[80:83]
	v_mfma_f32_16x16x32_bf16 v[72:75], v[128:131], v[168:171], v[72:75]
	v_mfma_f32_16x16x32_bf16 v[64:67], v[136:139], v[168:171], v[64:67]
	v_mfma_f32_16x16x32_bf16 v[120:123], v[132:135], v[148:151], v[120:123]
	v_mfma_f32_16x16x32_bf16 v[112:115], v[140:143], v[148:151], v[112:115]
	v_mfma_f32_16x16x32_bf16 v[104:107], v[132:135], v[156:159], v[104:107]
	v_mfma_f32_16x16x32_bf16 v[96:99], v[140:143], v[156:159], v[96:99]
	v_mfma_f32_16x16x32_bf16 v[88:91], v[132:135], v[164:167], v[88:91]
	v_mfma_f32_16x16x32_bf16 v[80:83], v[140:143], v[164:167], v[80:83]
	v_mfma_f32_16x16x32_bf16 v[72:75], v[132:135], v[172:175], v[72:75]
	v_mfma_f32_16x16x32_bf16 v[64:67], v[140:143], v[172:175], v[64:67]
	s_barrier
	s_add_i32 s30, 0, 0x1c000
	s_add_i32 s29, s29, s66
	v_add_u32_e32 v200, s30, v191
	s_mov_b32 m0, s29
	ds_read_b128 v[176:179], v200
	ds_read_b128 v[180:183], v200 offset:1024
	ds_read_b128 v[196:199], v200 offset:2048
	ds_read_b128 v[200:203], v200 offset:3072
	global_load_lds_dwordx4 v188, s[36:37]
	s_add_i32 m0, s29, 0x2000
	s_nop 0
	global_load_lds_dwordx4 v184, s[36:37]
	s_barrier
; #define PG8_STAGE(bufoff, gbase, voff) do { _Pragma("unroll") for (int _i = 0; _i < 2; ++_i) \
;         __builtin_amdgcn_global_load_lds((const unsigned*)((const char*)(gbase) + (voff)[_i]), (LAS unsigned*)(lds + (bufoff) + ldsw + _i * 8192), 16, 0, 0); } while (0)
; #define PG8_LDA(dst, b, h) do { _Pragma("unroll") for (int m = 0; m < 4; ++m) _Pragma("unroll") for (int k = 0; k < 2; ++k) dst[m][k] = *(const LAS bf16x8*)(lds + PG8_SA(b, h) + aoff + m * 2048 + k * 1024); } while (0)
; #define PG8_MMA(ai, bj, At, Bt) do { __builtin_amdgcn_s_setprio(1); _Pragma("unroll") for (int m = 0; m < 4; ++m) _Pragma("unroll") for (int n = 0; n < 2; ++n) _Pragma("unroll") for (int k = 0; k < 2; ++k) \
;         acc[ai][bj][m][n] = __builtin_amdgcn_mfma_f32_16x16x32_bf16(Bt[n][k], At[m][k], acc[ai][bj][m][n], 0, 0, 0); __builtin_amdgcn_s_setprio(0); } while (0)
; #define PG8_WAIT_V(n) asm volatile("s_waitcnt vmcnt(" #n ")" ::: "memory")
; #define PG8_WAIT_L(n) asm volatile("s_waitcnt lgkmcnt(" #n ")" ::: "memory")
; #define PG8_BAR __builtin_amdgcn_s_barrier()
; #define PG8_SCHED __builtin_amdgcn_sched_barrier(0)
; template <class Epi, class Sched>
; __device__ __forceinline__ void gemm_phase(LAS unsigned char* lds, const Gemm g, const Sched& S, const Epi& E) {
;     ...
;             PG8_BAR; PG8_WAIT_L(0); PG8_MMA(0, 1, At, B1); PG8_BAR;
;             PG8_LDA(At, 1, 1); PG8_STAGE(PG8_SA(1, 0), a3, voffA);
;             PG8_BAR; PG8_WAIT_L(0); PG8_MMA(1, 0, At, B0); PG8_BAR; PG8_SCHED;
;             PG8_STAGE(PG8_SB(1, 1), b3 + hstep, voffB);
;             PG8_WAIT_V(6); PG8_BAR; PG8_MMA(1, 1, At, B1); PG8_BAR;
;         }
	s_waitcnt lgkmcnt(0)
	s_waitcnt lgkmcnt(0)
	v_mfma_f32_16x16x32_bf16 v[124:127], v[176:179], v[144:147], v[124:127]
	v_mfma_f32_16x16x32_bf16 v[116:119], v[196:199], v[144:147], v[116:119]
	v_mfma_f32_16x16x32_bf16 v[108:111], v[176:179], v[152:155], v[108:111]
	v_mfma_f32_16x16x32_bf16 v[100:103], v[196:199], v[152:155], v[100:103]
	v_mfma_f32_16x16x32_bf16 v[92:95], v[176:179], v[160:163], v[92:95]
	v_mfma_f32_16x16x32_bf16 v[84:87], v[196:199], v[160:163], v[84:87]
	v_mfma_f32_16x16x32_bf16 v[76:79], v[176:179], v[168:171], v[76:79]
	v_mfma_f32_16x16x32_bf16 v[68:71], v[196:199], v[168:171], v[68:71]
	v_mfma_f32_16x16x32_bf16 v[124:127], v[180:183], v[148:151], v[124:127]
	v_mfma_f32_16x16x32_bf16 v[116:119], v[200:203], v[148:151], v[116:119]
	v_mfma_f32_16x16x32_bf16 v[108:111], v[180:183], v[156:159], v[108:111]
	v_mfma_f32_16x16x32_bf16 v[100:103], v[200:203], v[156:159], v[100:103]
	v_mfma_f32_16x16x32_bf16 v[92:95], v[180:183], v[164:167], v[92:95]
	v_mfma_f32_16x16x32_bf16 v[84:87], v[200:203], v[164:167], v[84:87]
	v_mfma_f32_16x16x32_bf16 v[76:79], v[180:183], v[172:175], v[76:79]
	v_mfma_f32_16x16x32_bf16 v[68:71], v[200:203], v[172:175], v[68:71]
	s_mov_b32 m0, s18
	s_barrier
	ds_read_b128 v[144:147], v235 offset:49152
	ds_read_b128 v[148:151], v235 offset:50176
	ds_read_b128 v[152:155], v235 offset:51200
	ds_read_b128 v[156:159], v235 offset:52224
	ds_read_b128 v[160:163], v235 offset:53248
	ds_read_b128 v[164:167], v235 offset:54272
	ds_read_b128 v[168:171], v235 offset:55296
	ds_read_b128 v[172:175], v235 offset:56320
	global_load_lds_dwordx4 v188, s[54:55]
	s_mov_b32 m0, s75
	s_nop 0
	global_load_lds_dwordx4 v184, s[54:55]
	s_barrier
	s_waitcnt lgkmcnt(0)
	s_waitcnt lgkmcnt(0)
	v_mfma_f32_16x16x32_bf16 v[56:59], v[128:131], v[144:147], v[56:59]
	v_mfma_f32_16x16x32_bf16 v[48:51], v[136:139], v[144:147], v[48:51]
	v_mfma_f32_16x16x32_bf16 v[40:43], v[128:131], v[152:155], v[40:43]
	v_mfma_f32_16x16x32_bf16 v[32:35], v[136:139], v[152:155], v[32:35]
	v_mfma_f32_16x16x32_bf16 v[24:27], v[128:131], v[160:163], v[24:27]
	v_mfma_f32_16x16x32_bf16 v[16:19], v[136:139], v[160:163], v[16:19]
	v_mfma_f32_16x16x32_bf16 v[8:11], v[128:131], v[168:171], v[8:11]
	v_mfma_f32_16x16x32_bf16 v[0:3], v[136:139], v[168:171], v[0:3]
	v_mfma_f32_16x16x32_bf16 v[56:59], v[132:135], v[148:151], v[56:59]
	v_mfma_f32_16x16x32_bf16 v[48:51], v[140:143], v[148:151], v[48:51]
	v_mfma_f32_16x16x32_bf16 v[40:43], v[132:135], v[156:159], v[40:43]
	v_mfma_f32_16x16x32_bf16 v[32:35], v[140:143], v[156:159], v[32:35]
	v_mfma_f32_16x16x32_bf16 v[24:27], v[132:135], v[164:167], v[24:27]
	v_mfma_f32_16x16x32_bf16 v[16:19], v[140:143], v[164:167], v[16:19]
	v_mfma_f32_16x16x32_bf16 v[8:11], v[132:135], v[172:175], v[8:11]
	v_mfma_f32_16x16x32_bf16 v[0:3], v[140:143], v[172:175], v[0:3]
	s_barrier
	s_add_i32 s29, s30, s66
	s_mov_b32 m0, s29
	s_nop 0
	global_load_lds_dwordx4 v188, s[84:85]
	s_add_i32 m0, s29, 0x2000
	s_nop 0
	global_load_lds_dwordx4 v184, s[84:85]
	s_waitcnt vmcnt(6)
	s_barrier
	v_mfma_f32_16x16x32_bf16 v[60:63], v[176:179], v[144:147], v[60:63]
	v_mfma_f32_16x16x32_bf16 v[52:55], v[196:199], v[144:147], v[52:55]
	v_mfma_f32_16x16x32_bf16 v[44:47], v[176:179], v[152:155], v[44:47]
	v_mfma_f32_16x16x32_bf16 v[36:39], v[196:199], v[152:155], v[36:39]
	v_mfma_f32_16x16x32_bf16 v[28:31], v[176:179], v[160:163], v[28:31]
	v_mfma_f32_16x16x32_bf16 v[20:23], v[196:199], v[160:163], v[20:23]
	v_mfma_f32_16x16x32_bf16 v[12:15], v[176:179], v[168:171], v[12:15]
	v_mfma_f32_16x16x32_bf16 v[4:7], v[196:199], v[168:171], v[4:7]
	v_mfma_f32_16x16x32_bf16 v[60:63], v[180:183], v[148:151], v[60:63]
	v_mfma_f32_16x16x32_bf16 v[52:55], v[200:203], v[148:151], v[52:55]
	v_mfma_f32_16x16x32_bf16 v[44:47], v[180:183], v[156:159], v[44:47]
	v_mfma_f32_16x16x32_bf16 v[36:39], v[200:203], v[156:159], v[36:39]
	v_mfma_f32_16x16x32_bf16 v[28:31], v[180:183], v[164:167], v[28:31]
	v_mfma_f32_16x16x32_bf16 v[20:23], v[200:203], v[164:167], v[20:23]
	v_mfma_f32_16x16x32_bf16 v[12:15], v[180:183], v[172:175], v[12:15]
	v_mfma_f32_16x16x32_bf16 v[4:7], v[200:203], v[172:175], v[4:7]
	s_add_u32 s24, s24, 0x100
	s_addc_u32 s25, s25, 0
	s_add_u32 s26, s26, 0x100
	s_addc_u32 s27, s27, 0
	s_cmp_ge_i32 s33, s74
	s_mov_b32 s29, s33
	s_barrier
	s_cbranch_scc0 .LBB0_232
	s_mov_b32 s42, s82
	s_branch .LBB0_235

; #define PG8_STAGE(bufoff, gbase, voff) do { _Pragma("unroll") for (int _i = 0; _i < 2; ++_i) \
;         __builtin_amdgcn_global_load_lds((const unsigned*)((const char*)(gbase) + (voff)[_i]), (LAS unsigned*)(lds + (bufoff) + ldsw + _i * 8192), 16, 0, 0); } while (0)
; #define PG8_LDA(dst, b, h) do { _Pragma("unroll") for (int m = 0; m < 4; ++m) _Pragma("unroll") for (int k = 0; k < 2; ++k) dst[m][k] = *(const LAS bf16x8*)(lds + PG8_SA(b, h) + aoff + m * 2048 + k * 1024); } while (0)
; #define PG8_LDB(dst, b, h) do { _Pragma("unroll") for (int n = 0; n < 2; ++n) _Pragma("unroll") for (int k = 0; k < 2; ++k) dst[n][k] = *(const LAS bf16x8*)(lds + PG8_SB(b, h) + boff + n * 2048 + k * 1024); } while (0)
; #define PG8_MMA(ai, bj, At, Bt) do { __builtin_amdgcn_s_setprio(1); _Pragma("unroll") for (int m = 0; m < 4; ++m) _Pragma("unroll") for (int n = 0; n < 2; ++n) _Pragma("unroll") for (int k = 0; k < 2; ++k) \
;         acc[ai][bj][m][n] = __builtin_amdgcn_mfma_f32_16x16x32_bf16(Bt[n][k], At[m][k], acc[ai][bj][m][n], 0, 0, 0); __builtin_amdgcn_s_setprio(0); } while (0)
; #define PG8_WAIT_V(n) asm volatile("s_waitcnt vmcnt(" #n ")" ::: "memory")
; #define PG8_WAIT_L(n) asm volatile("s_waitcnt lgkmcnt(" #n ")" ::: "memory")
; template <class Epi, class Sched>
; __device__ __forceinline__ void gemm_phase(LAS unsigned char* lds, const Gemm g, const Sched& S, const Epi& E) {
;     ...
;         for (int t = 0; t < nt; t += 2) {
;             const bool last = (t == nt - 2);
;             const char* a1 = cA + (size_t)(t + 1) * kstep;
;             const char* a2 = last ? nA : cA + (size_t)(t + 2) * kstep; const char* b2 = last ? nB : cB + (size_t)(t + 2) * kstep;
;             const char* a3 = a2 + kstep; const char* b3 = b2 + kstep;
;             PG8_LDB(B0, 0, 0); PG8_SCHED; PG8_LDA(At, 0, 0); PG8_STAGE(PG8_SA(1, 1), a1 + hstep, voffA);
;             PG8_WAIT_L(8); PG8_BAR; PG8_WAIT_L(0); PG8_MMA(0, 0, At, B0); PG8_BAR; PG8_SCHED;
;             PG8_LDB(B1, 0, 1); PG8_STAGE(PG8_SB(0, 0), b2, voffB);
;             PG8_BAR; PG8_WAIT_L(0); PG8_MMA(0, 1, At, B1); PG8_BAR;
;             PG8_LDA(At, 0, 1); PG8_STAGE(PG8_SA(0, 0), a2, voffA);
;             PG8_BAR; PG8_WAIT_L(0); PG8_MMA(1, 0, At, B0); PG8_BAR; PG8_SCHED;
;             PG8_STAGE(PG8_SB(0, 1), b2 + hstep, voffB);
;             PG8_WAIT_V(6); PG8_BAR; PG8_MMA(1, 1, At, B1); PG8_BAR;
.LBB0_339:
	s_add_i32 s30, s4, 2
	s_add_u32 s28, s0, 0x80
	s_addc_u32 s5, s1, 0
	s_add_i32 s31, 0, 0x10000
	v_add_u32_e32 v140, s31, v214
	ds_read_b128 v[128:131], v140
	ds_read_b128 v[132:135], v140 offset:1024
	ds_read_b128 v[136:139], v140 offset:2048
	ds_read_b128 v[140:143], v140 offset:3072
	s_cmp_eq_u32 s66, s4
	s_cselect_b32 s4, s18, s28
	s_cselect_b32 s5, s19, s5
	s_cselect_b32 s29, s27, s76
	s_cselect_b32 s28, s26, s75
	s_add_i32 m0, s50, 0xc000
	ds_read_b128 v[144:147], v221
	ds_read_b128 v[148:151], v221 offset:1024
	ds_read_b128 v[152:155], v221 offset:2048
	ds_read_b128 v[156:159], v221 offset:3072
	ds_read_b128 v[160:163], v221 offset:4096
	ds_read_b128 v[164:167], v221 offset:5120
	ds_read_b128 v[168:171], v221 offset:6144
	ds_read_b128 v[172:175], v221 offset:7168
	global_load_lds_dwordx4 v200, s[0:1]
	s_add_i32 m0, s50, 0xe000
	s_nop 0
	global_load_lds_dwordx4 v198, s[0:1]
	s_waitcnt lgkmcnt(8)
	s_barrier
	s_waitcnt lgkmcnt(0)
	s_waitcnt lgkmcnt(0)
	v_mfma_f32_16x16x32_bf16 v[120:123], v[128:131], v[144:147], v[120:123]
	v_mfma_f32_16x16x32_bf16 v[112:115], v[136:139], v[144:147], v[112:115]
	v_mfma_f32_16x16x32_bf16 v[104:107], v[128:131], v[152:155], v[104:107]
	v_mfma_f32_16x16x32_bf16 v[96:99], v[136:139], v[152:155], v[96:99]
	v_mfma_f32_16x16x32_bf16 v[88:91], v[128:131], v[160:163], v[88:91]
	v_mfma_f32_16x16x32_bf16 v[80:83], v[136:139], v[160:163], v[80:83]
	v_mfma_f32_16x16x32_bf16 v[72:75], v[128:131], v[168:171], v[72:75]
	v_mfma_f32_16x16x32_bf16 v[64:67], v[136:139], v[168:171], v[64:67]
	v_mfma_f32_16x16x32_bf16 v[120:123], v[132:135], v[148:151], v[120:123]
	v_mfma_f32_16x16x32_bf16 v[112:115], v[140:143], v[148:151], v[112:115]
	v_mfma_f32_16x16x32_bf16 v[104:107], v[132:135], v[156:159], v[104:107]
	v_mfma_f32_16x16x32_bf16 v[96:99], v[140:143], v[156:159], v[96:99]
	v_mfma_f32_16x16x32_bf16 v[88:91], v[132:135], v[164:167], v[88:91]
	v_mfma_f32_16x16x32_bf16 v[80:83], v[140:143], v[164:167], v[80:83]
	v_mfma_f32_16x16x32_bf16 v[72:75], v[132:135], v[172:175], v[72:75]
	v_mfma_f32_16x16x32_bf16 v[64:67], v[140:143], v[172:175], v[64:67]
	s_barrier
	s_add_i32 s33, 0, 0x14000
	s_add_i32 s31, s31, s34
	v_add_u32_e32 v188, s33, v214
	s_mov_b32 m0, s31
	ds_read_b128 v[176:179], v188
	ds_read_b128 v[180:183], v188 offset:1024
	ds_read_b128 v[184:187], v188 offset:2048
	ds_read_b128 v[202:205], v188 offset:3072
	s_add_u32 s36, s28, 0x80
	s_addc_u32 s37, s29, 0
	global_load_lds_dwordx4 v192, s[28:29]
	s_add_i32 m0, s31, 0x2000
	s_nop 0
	global_load_lds_dwordx4 v194, s[28:29]
	s_barrier
	s_waitcnt lgkmcnt(0)
	s_waitcnt lgkmcnt(0)
	v_mfma_f32_16x16x32_bf16 v[124:127], v[176:179], v[144:147], v[124:127]
	v_mfma_f32_16x16x32_bf16 v[116:119], v[184:187], v[144:147], v[116:119]
	v_mfma_f32_16x16x32_bf16 v[108:111], v[176:179], v[152:155], v[108:111]
	v_mfma_f32_16x16x32_bf16 v[100:103], v[184:187], v[152:155], v[100:103]
	v_mfma_f32_16x16x32_bf16 v[92:95], v[176:179], v[160:163], v[92:95]
	v_mfma_f32_16x16x32_bf16 v[84:87], v[184:187], v[160:163], v[84:87]
	v_mfma_f32_16x16x32_bf16 v[76:79], v[176:179], v[168:171], v[76:79]
	v_mfma_f32_16x16x32_bf16 v[68:71], v[184:187], v[168:171], v[68:71]
	v_mfma_f32_16x16x32_bf16 v[124:127], v[180:183], v[148:151], v[124:127]
	v_mfma_f32_16x16x32_bf16 v[116:119], v[202:205], v[148:151], v[116:119]
	v_mfma_f32_16x16x32_bf16 v[108:111], v[180:183], v[156:159], v[108:111]
	v_mfma_f32_16x16x32_bf16 v[100:103], v[202:205], v[156:159], v[100:103]
	v_mfma_f32_16x16x32_bf16 v[92:95], v[180:183], v[164:167], v[92:95]
	v_mfma_f32_16x16x32_bf16 v[84:87], v[202:205], v[164:167], v[84:87]
	v_mfma_f32_16x16x32_bf16 v[76:79], v[180:183], v[172:175], v[76:79]
	v_mfma_f32_16x16x32_bf16 v[68:71], v[202:205], v[172:175], v[68:71]
	s_mov_b32 m0, s50
	s_barrier
	ds_read_b128 v[144:147], v221 offset:16384
	ds_read_b128 v[148:151], v221 offset:17408
	ds_read_b128 v[152:155], v221 offset:18432
	ds_read_b128 v[156:159], v221 offset:19456
	ds_read_b128 v[160:163], v221 offset:20480
	ds_read_b128 v[164:167], v221 offset:21504
	ds_read_b128 v[168:171], v221 offset:22528
	ds_read_b128 v[172:175], v221 offset:23552
	s_add_u32 s54, s4, 0x80
	s_addc_u32 s55, s5, 0
	global_load_lds_dwordx4 v192, s[4:5]
	s_mov_b32 m0, s51
	s_nop 0
	global_load_lds_dwordx4 v194, s[4:5]
	s_barrier
	s_waitcnt lgkmcnt(0)
	s_waitcnt lgkmcnt(0)
	v_mfma_f32_16x16x32_bf16 v[60:63], v[128:131], v[144:147], v[60:63]
	v_mfma_f32_16x16x32_bf16 v[52:55], v[136:139], v[144:147], v[52:55]
	v_mfma_f32_16x16x32_bf16 v[44:47], v[128:131], v[152:155], v[44:47]
	v_mfma_f32_16x16x32_bf16 v[36:39], v[136:139], v[152:155], v[36:39]
	v_mfma_f32_16x16x32_bf16 v[28:31], v[128:131], v[160:163], v[28:31]
	v_mfma_f32_16x16x32_bf16 v[20:23], v[136:139], v[160:163], v[20:23]
	v_mfma_f32_16x16x32_bf16 v[12:15], v[128:131], v[168:171], v[12:15]
	v_mfma_f32_16x16x32_bf16 v[4:7], v[136:139], v[168:171], v[4:7]
	v_mfma_f32_16x16x32_bf16 v[60:63], v[132:135], v[148:151], v[60:63]
	v_mfma_f32_16x16x32_bf16 v[52:55], v[140:143], v[148:151], v[52:55]
	v_mfma_f32_16x16x32_bf16 v[44:47], v[132:135], v[156:159], v[44:47]
	v_mfma_f32_16x16x32_bf16 v[36:39], v[140:143], v[156:159], v[36:39]
	v_mfma_f32_16x16x32_bf16 v[28:31], v[132:135], v[164:167], v[28:31]
	v_mfma_f32_16x16x32_bf16 v[20:23], v[140:143], v[164:167], v[20:23]
	v_mfma_f32_16x16x32_bf16 v[12:15], v[132:135], v[172:175], v[12:15]
	v_mfma_f32_16x16x32_bf16 v[4:7], v[140:143], v[172:175], v[4:7]
	s_barrier
	s_add_u32 s28, s28, s20
	s_addc_u32 s29, s29, s21
	s_add_u32 s84, s28, 0x80
	s_addc_u32 s85, s29, 0
	s_add_i32 s31, s33, s34
	s_mov_b32 m0, s31
	s_nop 0
	global_load_lds_dwordx4 v192, s[28:29]
	s_add_i32 m0, s31, 0x2000
	s_nop 0
	global_load_lds_dwordx4 v194, s[28:29]
	s_waitcnt vmcnt(6)
	s_barrier
; #define PG8_STAGE(bufoff, gbase, voff) do { _Pragma("unroll") for (int _i = 0; _i < 2; ++_i) \
;         __builtin_amdgcn_global_load_lds((const unsigned*)((const char*)(gbase) + (voff)[_i]), (LAS unsigned*)(lds + (bufoff) + ldsw + _i * 8192), 16, 0, 0); } while (0)
; #define PG8_LDA(dst, b, h) do { _Pragma("unroll") for (int m = 0; m < 4; ++m) _Pragma("unroll") for (int k = 0; k < 2; ++k) dst[m][k] = *(const LAS bf16x8*)(lds + PG8_SA(b, h) + aoff + m * 2048 + k * 1024); } while (0)
; #define PG8_LDB(dst, b, h) do { _Pragma("unroll") for (int n = 0; n < 2; ++n) _Pragma("unroll") for (int k = 0; k < 2; ++k) dst[n][k] = *(const LAS bf16x8*)(lds + PG8_SB(b, h) + boff + n * 2048 + k * 1024); } while (0)
; #define PG8_MMA(ai, bj, At, Bt) do { __builtin_amdgcn_s_setprio(1); _Pragma("unroll") for (int m = 0; m < 4; ++m) _Pragma("unroll") for (int n = 0; n < 2; ++n) _Pragma("unroll") for (int k = 0; k < 2; ++k) \
;         acc[ai][bj][m][n] = __builtin_amdgcn_mfma_f32_16x16x32_bf16(Bt[n][k], At[m][k], acc[ai][bj][m][n], 0, 0, 0); __builtin_amdgcn_s_setprio(0); } while (0)
; #define PG8_WAIT_V(n) asm volatile("s_waitcnt vmcnt(" #n ")" ::: "memory")
; #define PG8_WAIT_L(n) asm volatile("s_waitcnt lgkmcnt(" #n ")" ::: "memory")
; #define PG8_BAR __builtin_amdgcn_s_barrier()
; #define PG8_SCHED __builtin_amdgcn_sched_barrier(0)
; template <class Epi, class Sched>
; __device__ __forceinline__ void gemm_phase(LAS unsigned char* lds, const Gemm g, const Sched& S, const Epi& E) {
;     ...
;             PG8_WAIT_V(6); PG8_BAR; PG8_MMA(1, 1, At, B1); PG8_BAR;
;             PG8_LDB(B0, 1, 0); PG8_SCHED; PG8_LDA(At, 1, 0); PG8_STAGE(PG8_SA(0, 1), a2 + hstep, voffA);
;             PG8_WAIT_L(8); PG8_BAR; PG8_WAIT_L(0); PG8_MMA(0, 0, At, B0); PG8_BAR; PG8_SCHED;
;             PG8_LDB(B1, 1, 1); PG8_STAGE(PG8_SB(1, 0), b3, voffB);
	v_mfma_f32_16x16x32_bf16 v[56:59], v[176:179], v[144:147], v[56:59]
	v_mfma_f32_16x16x32_bf16 v[48:51], v[184:187], v[144:147], v[48:51]
	v_mfma_f32_16x16x32_bf16 v[40:43], v[176:179], v[152:155], v[40:43]
	v_mfma_f32_16x16x32_bf16 v[32:35], v[184:187], v[152:155], v[32:35]
	v_mfma_f32_16x16x32_bf16 v[24:27], v[176:179], v[160:163], v[24:27]
	v_mfma_f32_16x16x32_bf16 v[16:19], v[184:187], v[160:163], v[16:19]
	v_mfma_f32_16x16x32_bf16 v[8:11], v[176:179], v[168:171], v[8:11]
	v_mfma_f32_16x16x32_bf16 v[0:3], v[184:187], v[168:171], v[0:3]
	v_mfma_f32_16x16x32_bf16 v[56:59], v[180:183], v[148:151], v[56:59]
	v_mfma_f32_16x16x32_bf16 v[48:51], v[202:205], v[148:151], v[48:51]
	v_mfma_f32_16x16x32_bf16 v[40:43], v[180:183], v[156:159], v[40:43]
	v_mfma_f32_16x16x32_bf16 v[32:35], v[202:205], v[156:159], v[32:35]
	v_mfma_f32_16x16x32_bf16 v[24:27], v[180:183], v[164:167], v[24:27]
	v_mfma_f32_16x16x32_bf16 v[16:19], v[202:205], v[164:167], v[16:19]
	v_mfma_f32_16x16x32_bf16 v[8:11], v[180:183], v[172:175], v[8:11]
	v_mfma_f32_16x16x32_bf16 v[0:3], v[202:205], v[172:175], v[0:3]
	s_add_i32 s28, 0, 0x18000
	v_add_u32_e32 v140, s28, v214
	s_barrier
	ds_read_b128 v[128:131], v140
	ds_read_b128 v[132:135], v140 offset:1024
	ds_read_b128 v[136:139], v140 offset:2048
	ds_read_b128 v[140:143], v140 offset:3072
	s_add_u32 s4, s4, s20
	s_addc_u32 s5, s5, s21
	s_mov_b32 m0, s60
	ds_read_b128 v[144:147], v221 offset:32768
	ds_read_b128 v[148:151], v221 offset:33792
	ds_read_b128 v[152:155], v221 offset:34816
	ds_read_b128 v[156:159], v221 offset:35840
	ds_read_b128 v[160:163], v221 offset:36864
	ds_read_b128 v[164:167], v221 offset:37888
	ds_read_b128 v[168:171], v221 offset:38912
	ds_read_b128 v[172:175], v221 offset:39936
	global_load_lds_dwordx4 v192, s[4:5]
	s_mov_b32 m0, s61
	s_nop 0
	global_load_lds_dwordx4 v194, s[4:5]
	s_waitcnt lgkmcnt(8)
	s_barrier
	s_waitcnt lgkmcnt(0)
	s_waitcnt lgkmcnt(0)
	v_mfma_f32_16x16x32_bf16 v[120:123], v[128:131], v[144:147], v[120:123]
	v_mfma_f32_16x16x32_bf16 v[112:115], v[136:139], v[144:147], v[112:115]
	v_mfma_f32_16x16x32_bf16 v[104:107], v[128:131], v[152:155], v[104:107]
	v_mfma_f32_16x16x32_bf16 v[96:99], v[136:139], v[152:155], v[96:99]
	v_mfma_f32_16x16x32_bf16 v[88:91], v[128:131], v[160:163], v[88:91]
	v_mfma_f32_16x16x32_bf16 v[80:83], v[136:139], v[160:163], v[80:83]
	v_mfma_f32_16x16x32_bf16 v[72:75], v[128:131], v[168:171], v[72:75]
	v_mfma_f32_16x16x32_bf16 v[64:67], v[136:139], v[168:171], v[64:67]
	v_mfma_f32_16x16x32_bf16 v[120:123], v[132:135], v[148:151], v[120:123]
	v_mfma_f32_16x16x32_bf16 v[112:115], v[140:143], v[148:151], v[112:115]
	v_mfma_f32_16x16x32_bf16 v[104:107], v[132:135], v[156:159], v[104:107]
	v_mfma_f32_16x16x32_bf16 v[96:99], v[140:143], v[156:159], v[96:99]
	v_mfma_f32_16x16x32_bf16 v[88:91], v[132:135], v[164:167], v[88:91]
	v_mfma_f32_16x16x32_bf16 v[80:83], v[140:143], v[164:167], v[80:83]
	v_mfma_f32_16x16x32_bf16 v[72:75], v[132:135], v[172:175], v[72:75]
	v_mfma_f32_16x16x32_bf16 v[64:67], v[140:143], v[172:175], v[64:67]
	s_barrier
	s_add_i32 s4, 0, 0x1c000
	s_add_i32 s5, s28, s34
	v_add_u32_e32 v188, s4, v214
	s_mov_b32 m0, s5
	ds_read_b128 v[176:179], v188
	ds_read_b128 v[180:183], v188 offset:1024
	ds_read_b128 v[184:187], v188 offset:2048
	ds_read_b128 v[202:205], v188 offset:3072
	global_load_lds_dwordx4 v192, s[36:37]
	s_add_i32 m0, s5, 0x2000
	s_nop 0
	global_load_lds_dwordx4 v194, s[36:37]
	s_barrier
; #define PG8_STAGE(bufoff, gbase, voff) do { _Pragma("unroll") for (int _i = 0; _i < 2; ++_i) \
;         __builtin_amdgcn_global_load_lds((const unsigned*)((const char*)(gbase) + (voff)[_i]), (LAS unsigned*)(lds + (bufoff) + ldsw + _i * 8192), 16, 0, 0); } while (0)
; #define PG8_LDA(dst, b, h) do { _Pragma("unroll") for (int m = 0; m < 4; ++m) _Pragma("unroll") for (int k = 0; k < 2; ++k) dst[m][k] = *(const LAS bf16x8*)(lds + PG8_SA(b, h) + aoff + m * 2048 + k * 1024); } while (0)
; #define PG8_MMA(ai, bj, At, Bt) do { __builtin_amdgcn_s_setprio(1); _Pragma("unroll") for (int m = 0; m < 4; ++m) _Pragma("unroll") for (int n = 0; n < 2; ++n) _Pragma("unroll") for (int k = 0; k < 2; ++k) \
;         acc[ai][bj][m][n] = __builtin_amdgcn_mfma_f32_16x16x32_bf16(Bt[n][k], At[m][k], acc[ai][bj][m][n], 0, 0, 0); __builtin_amdgcn_s_setprio(0); } while (0)
; #define PG8_WAIT_V(n) asm volatile("s_waitcnt vmcnt(" #n ")" ::: "memory")
; #define PG8_WAIT_L(n) asm volatile("s_waitcnt lgkmcnt(" #n ")" ::: "memory")
; #define PG8_BAR __builtin_amdgcn_s_barrier()
; #define PG8_SCHED __builtin_amdgcn_sched_barrier(0)
; template <class Epi, class Sched>
; __device__ __forceinline__ void gemm_phase(LAS unsigned char* lds, const Gemm g, const Sched& S, const Epi& E) {
;     ...
;             PG8_BAR; PG8_WAIT_L(0); PG8_MMA(0, 1, At, B1); PG8_BAR;
;             PG8_LDA(At, 1, 1); PG8_STAGE(PG8_SA(1, 0), a3, voffA);
;             PG8_BAR; PG8_WAIT_L(0); PG8_MMA(1, 0, At, B0); PG8_BAR; PG8_SCHED;
;             PG8_STAGE(PG8_SB(1, 1), b3 + hstep, voffB);
;             PG8_WAIT_V(6); PG8_BAR; PG8_MMA(1, 1, At, B1); PG8_BAR;
;         }
	s_waitcnt lgkmcnt(0)
	s_waitcnt lgkmcnt(0)
	v_mfma_f32_16x16x32_bf16 v[124:127], v[176:179], v[144:147], v[124:127]
	v_mfma_f32_16x16x32_bf16 v[116:119], v[184:187], v[144:147], v[116:119]
	v_mfma_f32_16x16x32_bf16 v[108:111], v[176:179], v[152:155], v[108:111]
	v_mfma_f32_16x16x32_bf16 v[100:103], v[184:187], v[152:155], v[100:103]
	v_mfma_f32_16x16x32_bf16 v[92:95], v[176:179], v[160:163], v[92:95]
	v_mfma_f32_16x16x32_bf16 v[84:87], v[184:187], v[160:163], v[84:87]
	v_mfma_f32_16x16x32_bf16 v[76:79], v[176:179], v[168:171], v[76:79]
	v_mfma_f32_16x16x32_bf16 v[68:71], v[184:187], v[168:171], v[68:71]
	v_mfma_f32_16x16x32_bf16 v[124:127], v[180:183], v[148:151], v[124:127]
	v_mfma_f32_16x16x32_bf16 v[116:119], v[202:205], v[148:151], v[116:119]
	v_mfma_f32_16x16x32_bf16 v[108:111], v[180:183], v[156:159], v[108:111]
	v_mfma_f32_16x16x32_bf16 v[100:103], v[202:205], v[156:159], v[100:103]
	v_mfma_f32_16x16x32_bf16 v[92:95], v[180:183], v[164:167], v[92:95]
	v_mfma_f32_16x16x32_bf16 v[84:87], v[202:205], v[164:167], v[84:87]
	v_mfma_f32_16x16x32_bf16 v[76:79], v[180:183], v[172:175], v[76:79]
	v_mfma_f32_16x16x32_bf16 v[68:71], v[202:205], v[172:175], v[68:71]
	s_mov_b32 m0, s62
	s_barrier
	ds_read_b128 v[144:147], v221 offset:49152
	ds_read_b128 v[148:151], v221 offset:50176
	ds_read_b128 v[152:155], v221 offset:51200
	ds_read_b128 v[156:159], v221 offset:52224
	ds_read_b128 v[160:163], v221 offset:53248
	ds_read_b128 v[164:167], v221 offset:54272
	ds_read_b128 v[168:171], v221 offset:55296
	ds_read_b128 v[172:175], v221 offset:56320
	global_load_lds_dwordx4 v192, s[54:55]
	s_mov_b32 m0, s63
	s_nop 0
	global_load_lds_dwordx4 v194, s[54:55]
	s_barrier
	s_waitcnt lgkmcnt(0)
	s_waitcnt lgkmcnt(0)
	v_mfma_f32_16x16x32_bf16 v[60:63], v[128:131], v[144:147], v[60:63]
	v_mfma_f32_16x16x32_bf16 v[52:55], v[136:139], v[144:147], v[52:55]
	v_mfma_f32_16x16x32_bf16 v[44:47], v[128:131], v[152:155], v[44:47]
	v_mfma_f32_16x16x32_bf16 v[36:39], v[136:139], v[152:155], v[36:39]
	v_mfma_f32_16x16x32_bf16 v[28:31], v[128:131], v[160:163], v[28:31]
	v_mfma_f32_16x16x32_bf16 v[20:23], v[136:139], v[160:163], v[20:23]
	v_mfma_f32_16x16x32_bf16 v[12:15], v[128:131], v[168:171], v[12:15]
	v_mfma_f32_16x16x32_bf16 v[4:7], v[136:139], v[168:171], v[4:7]
	v_mfma_f32_16x16x32_bf16 v[60:63], v[132:135], v[148:151], v[60:63]
	v_mfma_f32_16x16x32_bf16 v[52:55], v[140:143], v[148:151], v[52:55]
	v_mfma_f32_16x16x32_bf16 v[44:47], v[132:135], v[156:159], v[44:47]
	v_mfma_f32_16x16x32_bf16 v[36:39], v[140:143], v[156:159], v[36:39]
	v_mfma_f32_16x16x32_bf16 v[28:31], v[132:135], v[164:167], v[28:31]
	v_mfma_f32_16x16x32_bf16 v[20:23], v[140:143], v[164:167], v[20:23]
	v_mfma_f32_16x16x32_bf16 v[12:15], v[132:135], v[172:175], v[12:15]
	v_mfma_f32_16x16x32_bf16 v[4:7], v[140:143], v[172:175], v[4:7]
	s_barrier
	s_add_i32 s4, s4, s34
	s_mov_b32 m0, s4
	s_nop 0
	global_load_lds_dwordx4 v192, s[84:85]
	s_add_i32 m0, s4, 0x2000
	s_nop 0
	global_load_lds_dwordx4 v194, s[84:85]
	s_waitcnt vmcnt(6)
	s_barrier
	v_mfma_f32_16x16x32_bf16 v[56:59], v[176:179], v[144:147], v[56:59]
	v_mfma_f32_16x16x32_bf16 v[48:51], v[184:187], v[144:147], v[48:51]
	v_mfma_f32_16x16x32_bf16 v[40:43], v[176:179], v[152:155], v[40:43]
	v_mfma_f32_16x16x32_bf16 v[32:35], v[184:187], v[152:155], v[32:35]
	v_mfma_f32_16x16x32_bf16 v[24:27], v[176:179], v[160:163], v[24:27]
	v_mfma_f32_16x16x32_bf16 v[16:19], v[184:187], v[160:163], v[16:19]
	v_mfma_f32_16x16x32_bf16 v[8:11], v[176:179], v[168:171], v[8:11]
	v_mfma_f32_16x16x32_bf16 v[0:3], v[184:187], v[168:171], v[0:3]
	v_mfma_f32_16x16x32_bf16 v[56:59], v[180:183], v[148:151], v[56:59]
	v_mfma_f32_16x16x32_bf16 v[48:51], v[202:205], v[148:151], v[48:51]
	v_mfma_f32_16x16x32_bf16 v[40:43], v[180:183], v[156:159], v[40:43]
	v_mfma_f32_16x16x32_bf16 v[32:35], v[202:205], v[156:159], v[32:35]
	v_mfma_f32_16x16x32_bf16 v[24:27], v[180:183], v[164:167], v[24:27]
	v_mfma_f32_16x16x32_bf16 v[16:19], v[202:205], v[164:167], v[16:19]
	v_mfma_f32_16x16x32_bf16 v[8:11], v[180:183], v[172:175], v[8:11]
	v_mfma_f32_16x16x32_bf16 v[0:3], v[202:205], v[172:175], v[0:3]
	s_add_u32 s75, s75, 0x100
	s_addc_u32 s76, s76, 0
	s_add_u32 s0, s0, 0x100
	s_addc_u32 s1, s1, 0
	s_cmp_ge_i32 s30, s13
	s_mov_b32 s4, s30
	s_barrier
	s_cbranch_scc0 .LBB0_339
	s_mov_b32 s33, 0x200000
	s_cmp_lt_i32 s15, 2
	s_cbranch_scc1 .LBB0_345

; #define LAS __attribute__((address_space(3)))
; __device__ __forceinline__ unsigned xb_add(unsigned* p, unsigned v) { return __hip_atomic_fetch_add(p, v, __ATOMIC_RELAXED, __HIP_MEMORY_SCOPE_AGENT); }
; __device__ __forceinline__ unsigned xb_xcc_id() { return (unsigned)__builtin_amdgcn_s_getreg((3 << 11) | 20) & 0xFu; }
; __device__ __forceinline__ void xcd_barrier(unsigned char* ws, unsigned char* shm) {
;     XcdBarrier b; b.bar = (unsigned*)(ws + OFF_BAR); b.x = xb_xcc_id(); b.st = (volatile LAS unsigned*)((LAS unsigned char*)shm + LDS_PHASE_BYTES);
;     asm volatile("s_waitcnt vmcnt(0) lgkmcnt(0)" ::: "memory");
;     __syncthreads();
;     if (threadIdx.x == 0) {
;         unsigned* bar = b.bar;
;         __builtin_amdgcn_s_waitcnt(0);
;         unsigned nloc = b.st[0], nx = b.st[1];
;         if (nloc == 0u) { xcd_barrier_complete(bar, b.x, nloc, nx); b.st[0] = nloc; b.st[1] = nx; }
;         const unsigned old = xb_add(&bar[XB_XSUB(b.x)], 1u);
;         const unsigned gen = old / nloc;
; __global__ void __launch_bounds__(512, 2) fwd_megakernel(Params p, int ph_lo, int ph_hi) {
;     ...
;         if (ph + 1 < ph_hi || rp_ + 1 < nrep_) xcd_barrier(ws, shm);
.LBB0_549:
	s_mov_b32 s36, 0x16000
	s_mov_b32 s37, 0x18000
	s_mov_b32 s54, 0x12000
	s_mov_b32 s55, 0x14000
	s_mov_b64 s[84:85], 0x2000
	v_readlane_b32 s0, v254, 7
	s_add_i32 s60, s60, 1
	v_readlane_b32 s1, v254, 8
	s_cmp_ge_i32 s60, s1
	s_mov_b64 s[0:1], -1
	s_cbranch_scc1 .LBB0_146
	s_getreg_b32 s0, hwreg(HW_REG_XCC_ID, 0, 4)
	s_waitcnt vmcnt(0) lgkmcnt(0)
	s_waitcnt vmcnt(0) lgkmcnt(0)
	s_barrier
	s_mov_b64 s[6:7], exec
	v_readlane_b32 s4, v254, 5
	v_readlane_b32 s5, v254, 6
	s_and_b64 s[4:5], s[6:7], s[4:5]
	s_mov_b64 exec, s[4:5]
	s_cbranch_execz .LBB0_145
	v_readlane_b32 s1, v254, 55
	s_waitcnt vmcnt(0) expcnt(0) lgkmcnt(0)
	s_and_b32 s33, s0, 15
	v_mov_b32_e32 v0, s1
	ds_read_b32 v2, v0
	v_readlane_b32 s1, v254, 56
	s_waitcnt lgkmcnt(0)
	v_cmp_ne_u32_e32 vcc, 0, v2
	v_mov_b32_e32 v0, s1
	ds_read_b32 v0, v0
	s_cbranch_vccnz .LBB0_565
	v_writelane_b32 v255, s60, 12
	s_mov_b32 s46, 1
	s_mov_b64 s[70:71], 0
	v_writelane_b32 v255, s61, 13
	s_nop 0
	v_readlane_b32 s44, v255, 6
	v_readlane_b32 s45, v255, 7
	s_add_u32 s0, s44, 0x3ec30200
	s_addc_u32 s1, s45, 0
	s_add_u32 s4, s44, 0x3ec30400
	s_addc_u32 s5, s45, 0
	s_add_u32 s8, s44, 0x3ec30500
	s_addc_u32 s9, s45, 0
	s_add_u32 s10, s44, 0x3ec30600
	s_addc_u32 s11, s45, 0
	s_add_u32 s12, s44, 0x3ec30700
	s_addc_u32 s13, s45, 0
	s_add_u32 s14, s44, 0x3ec30800
	s_addc_u32 s15, s45, 0
	s_add_u32 s16, s44, 0x3ec30900
	s_addc_u32 s17, s45, 0
	s_add_u32 s18, s44, 0x3ec30a00
	s_addc_u32 s19, s45, 0
	s_add_u32 s20, s44, 0x3ec30b00
	s_addc_u32 s21, s45, 0
	s_add_u32 s22, s44, 0x3ec30c00
	s_addc_u32 s23, s45, 0
	s_add_u32 s24, s44, 0x3ec30d00
	s_addc_u32 s25, s45, 0
	s_add_u32 s26, s44, 0x3ec30e00
	s_addc_u32 s27, s45, 0
	s_add_u32 s28, s44, 0x3ec30f00
	s_addc_u32 s29, s45, 0
	s_add_u32 s30, s44, 0x3ec31000
	s_addc_u32 s31, s45, 0
	s_add_u32 s34, s44, 0x3ec31100
	s_addc_u32 s35, s45, 0
	s_add_u32 s62, s44, 0x3ec31200
	s_addc_u32 s63, s45, 0
	s_add_u32 s68, s44, 0x3ec31300
	s_addc_u32 s69, s45, 0
	s_branch .LBB0_555
